# GDN scan: next-chunk loads address through scalar bases + 32-bit lane offsets (14 VALU and 8 s_nop fewer per step)
# baseline (speedup 1.0000x reference)
; DI int otid() { int t = threadIdx.x; asm volatile("" : "+v"(t)); return t; }
; DI void gdn_scan_item(const P& p, int item, unsigned char* smem) {
;     const int seq = (item & 7) * 4 + (item >> 5), cq = (item >> 3) & 3;
;     const int dir = seq >> 4, b = (seq >> 2) & 3, h = seq & 3;
;     constexpr int BUFB = 3 * 17408 + 9216 + 5120;
;     bf16_t* sVN = (bf16_t*)(smem + 2 * BUFB);
;     float* sdec = (float*)(smem + 2 * BUFB + 5120);
;     const bf16_t* U = (const bf16_t*)(p.ws + WS_GDN_U); const bf16_t* W = (const bf16_t*)(p.ws + WS_GDN_W); const bf16_t* QI = (const bf16_t*)(p.ws + WS_GDN_QI); const bf16_t* KO = (const bf16_t*)(p.ws + WS_GDN_KO);
;     const bf16_t* AT = (const bf16_t*)(p.ws + WS_GDN_AT); const float* DC = (const float*)(p.ws + WS_GDN_DC);
;     bf16_t* OG = (bf16_t*)(p.ws + WS_NBUF) + (size_t)(2 + dir) * NROW * 512;
;     const int tid = otid(), w = tid >> 6, lane = tid & 63, l15 = lane & 15, g = lane >> 4, q4 = l15 >> 2, p4 = l15 & 3;
;     const int mt = w >> 1, nt = w & 1;
;     auto loadr = [&](GdnRegs& R, int c) {
;         if (c >= 36) return;
;         u32x4* rr = R.r;
; #pragma unroll
;         for (int k = 0; k < 2; ++k) {
;             const int e = tid + 512 * k, r = e >> 4, ch = e & 15; const size_t off = ((size_t)seq * PT + 64 * c + r) * 128 + 8 * ch;
;             rr[k] = *(const u32x4*)(W + off); rr[2 + k] = *(const u32x4*)(QI + off); rr[4 + k] = *(const u32x4*)(KO + off);
;         }
;         { const int r = tid >> 3, ch = tid & 7; rr[6] = *(const u32x4*)(AT + (((size_t)seq * 36 + c) * 64 + r) * 64 + 8 * ch); }
;         if (tid < 256) { const int r = tid >> 2, ch = tid & 3; rr[7] = __builtin_nontemporal_load((const u32x4*)(U + ((size_t)seq * PT + 64 * c + r) * 128 + 32 * cq + 8 * ch)); }
;     };
;     auto storel = [&](const GdnRegs& R, int buf) {
;         const u32x4* rr = R.r;
;         bf16_t* sW = (bf16_t*)(smem + buf * BUFB); bf16_t* sQI = sW + 64 * 136; bf16_t* sKO = sQI + 64 * 136; bf16_t* sAT = sKO + 64 * 136; bf16_t* sU = sAT + 64 * 72;
; #pragma unroll
;         for (int k = 0; k < 2; ++k) {
;             const int e = tid + 512 * k, r = e >> 4, ch = e & 15; const int off = r * 136 + 8 * ch;
;             *(u32x4*)(sW + off) = rr[k]; *(u32x4*)(sQI + off) = rr[2 + k]; *(u32x4*)(sKO + off) = rr[4 + k];
;         }
;         { const int r = tid >> 3, ch = tid & 7; *(u32x4*)(sAT + r * 72 + 8 * ch) = rr[6]; }
.LBB0_499:
	s_or_b64 exec, exec, s[38:39]
	s_lshr_b32 s2, s22, 4
	s_and_b32 s3, s56, 3
	s_add_i32 s6, s57, 0x20800
	s_mul_i32 s2, s2, 0x900000
	s_add_u32 s2, s46, s2
	s_addc_u32 s4, s47, 0
	s_cmp_lt_u32 s22, 16
	s_cselect_b64 s[38:39], -1, 0
	s_lshl_b32 s5, s24, 8
	s_add_u32 s7, s2, s5
	s_movk_i32 s9, 0x88
	s_addc_u32 s8, s4, 0
	v_mad_u64_u32 v[120:121], s[4:5], v98, s9, v[132:133]
	v_mad_u64_u32 v[122:123], s[4:5], v100, s9, v[132:133]
	v_and_b32_e32 v108, 15, v96
	s_movk_i32 s4, 0x48
	v_lshrrev_b32_e32 v112, 4, v110
	v_mul_lo_u32 v114, v106, s4
	v_lshl_add_u32 v117, v110, 4, v111
	v_lshl_or_b32 v110, v97, 4, v108
	s_movk_i32 s4, 0x50
	v_lshlrev_b32_e32 v132, 5, v105
	v_lshlrev_b32_e32 v115, 4, v105
	v_mul_lo_u32 v106, v110, s4
	v_lshlrev_b32_e32 v124, 3, v112
	v_add_u32_e32 v105, s6, v132
	v_add3_u32 v123, v105, v106, v124
	v_lshlrev_b32_e32 v106, 2, v96
	v_bfe_u32 v113, v96, 2, 2
	v_and_b32_e32 v157, 12, v106
	v_lshlrev_b32_e32 v107, 13, v97
	v_lshlrev_b32_e32 v111, 2, v112
	v_lshl_add_u32 v112, v157, 1, v105
	v_or_b32_e32 v105, 4, v113
	v_lshl_or_b32 v107, v108, 9, v107
	s_lshl_b32 s2, s3, 11
	s_lshl_b32 s3, s3, 8
	v_or_b32_e32 v106, v124, v105
	v_sub_u32_e32 v109, 0, v107
	s_bitset1_b32 s3, 13
	v_mul_u32_u24_e32 v150, 0x50, v106
	v_or_b32_e32 v106, 32, v124
	v_or_b32_e32 v134, v124, v113
	v_or_b32_e32 v113, v106, v113
	v_or_b32_e32 v105, v106, v105
	s_add_u32 s4, s7, s26
	v_cndmask_b32_e64 v106, v109, v107, s[38:39]
	s_addc_u32 s5, s8, 0
	v_ashrrev_i32_e32 v107, 31, v106
	v_lshl_add_u64 v[106:107], v[106:107], 1, s[4:5]
	v_lshl_add_u64 v[106:107], v[106:107], 0, v[132:133]
	v_mov_b32_e32 v125, v133
	v_lshl_add_u64 v[106:107], v[106:107], 0, v[124:125]
	s_mov_b64 s[4:5], 0x5a3c000
	v_lshl_add_u64 v[126:127], v[106:107], 0, s[4:5]
	s_movk_i32 s4, 0xff40
	v_mul_lo_u32 v158, v110, s4
	s_movk_i32 s4, 0xc0
	s_add_i32 s24, s24, s22
	v_and_b32_e32 v96, 7, v96
	v_mul_lo_u32 v121, v110, s9
	v_lshlrev_b32_e32 v125, 5, v97
	v_mul_lo_u32 v159, v110, s4
	v_lshlrev_b32_e32 v97, 7, v110
	v_mad_u64_u32 v[102:103], s[4:5], s24, v181, v[102:103]
	v_lshlrev_b32_e32 v132, 4, v96
	v_readlane_b32 s8, v254, 26
	v_mul_u32_u24_e32 v152, 0x50, v105
	v_ashrrev_i32_e32 v105, 31, v104
	v_sub_u32_e32 v160, 0, v97
	v_lshl_add_u64 v[96:97], v[102:103], 0, v[132:133]
	v_readlane_b32 s9, v254, 27
	v_mul_u32_u24_e32 v135, 0x50, v134
	v_mul_u32_u24_e32 v151, 0x50, v113
	v_lshl_add_u64 v[142:143], s[8:9], 0, v[96:97]
	v_lshlrev_b64 v[96:97], 8, v[104:105]
	v_mad_u64_u32 v[96:97], s[4:5], s24, v182, v[96:97]
	s_lshl_b32 s4, s56, 3
	s_and_b32 s4, s4, 0xc0
	v_or_b32_e32 v96, s4, v96
	v_lshl_add_u64 v[96:97], v[118:119], 1, v[96:97]
	v_lshl_add_u64 v[144:145], s[8:9], 0, v[96:97]
	v_lshlrev_b64 v[96:97], 8, v[100:101]
	v_mad_u64_u32 v[96:97], s[4:5], s24, v182, v[96:97]
	v_lshlrev_b32_e32 v100, 4, v108
	v_or_b32_e32 v96, v96, v100
	v_lshl_add_u64 v[146:147], s[8:9], 0, v[96:97]
	v_lshlrev_b64 v[96:97], 8, v[98:99]
	v_mad_u64_u32 v[96:97], s[4:5], s24, v182, v[96:97]
	v_or_b32_e32 v96, v96, v100
	v_mul_u32_u24_e32 v106, 0x88, v134
	v_mul_u32_u24_e32 v107, 0x88, v113
	v_mul_lo_u32 v109, v104, 40
	v_lshl_add_u64 v[148:149], s[8:9], 0, v[96:97]
	v_mov_b32_e32 v96, 0
	s_mov_b32 s27, -3
	s_movk_i32 s22, 0x80
	s_movk_i32 s24, 0x87f
	v_lshlrev_b32_e32 v119, 1, v114
	v_lshlrev_b32_e32 v161, 1, v109
	v_lshlrev_b32_e32 v162, 1, v111
	v_lshlrev_b32_e32 v163, 1, v115
	v_add_u32_e32 v164, v112, v135
	v_add_u32_e32 v165, v112, v150
	v_add_u32_e32 v183, v112, v151
	v_add_u32_e32 v184, v112, v152
	v_lshlrev_b32_e32 v185, 1, v106
	v_lshlrev_b32_e32 v186, 1, v107
	v_mov_b32_e32 v97, v96
	v_mov_b32_e32 v98, v96
	v_mov_b32_e32 v99, v96
	v_mov_b32_e32 v100, v96
	v_mov_b32_e32 v101, v96
	v_mov_b32_e32 v102, v96
	v_mov_b32_e32 v103, v96
	v_readlane_b32 s10, v254, 28
	v_readlane_b32 s11, v254, 29
	v_readlane_b32 s98, v254, 26
	v_readlane_b32 s99, v254, 27
	s_nop 0
	v_subrev_u32_e32 v212, s98, v148
	v_subrev_u32_e32 v213, s98, v146
	v_subrev_u32_e32 v214, s98, v142
	v_subrev_u32_e32 v215, s98, v144
	s_branch .LBB0_501
; DI float lo16(unsigned u) { return __uint_as_float(u << 16); }
; DI void gdn_scan_item(const P& p, int item, unsigned char* smem) {
;     ...
;     auto step = [&](GdnRegs& R, int c) {
;         storel(R, c & 1);
;         __syncthreads();
;         loadr(R, c + 3);
;         const bf16_t* sW = (const bf16_t*)(smem + (c & 1) * BUFB); const bf16_t* sQI = sW + 64 * 136; const bf16_t* sKO = sQI + 64 * 136; const bf16_t* sAT = sKO + 64 * 136; const bf16_t* sU = sAT + 64 * 72;
;         const float dec = sdec[c];
;         bf16x8 Bs[4];
; #pragma unroll
;         for (int ks = 0; ks < 4; ++ks) Bs[ks] = __builtin_bit_cast(bf16x8, sBS[(nt * 4 + ks) * 64 + lane]);
;         {
;             f32x4 acc = (f32x4){0.f, 0.f, 0.f, 0.f};
; #pragma unroll
;             for (int ks = 0; ks < 4; ++ks) { const bf16_t* r0 = sW + (16 * mt + l15) * 136 + 32 * ks + 4 * g; acc = mfma16(Bs[ks], ld4x2(r0, r0 + 16), acc); }
;             {
;                 const u32x2 uu = *(const u32x2*)(sU + (16 * mt + l15) * 40 + 16 * nt + 4 * g);
;                 u32x2 vv; vv.x = pk2(lo16(uu.x) - acc[0], hi16(uu.x) - acc[1]); vv.y = pk2(lo16(uu.y) - acc[2], hi16(uu.y) - acc[3]);
;                 *(u32x2*)(sVN + (16 * mt + l15) * 40 + 16 * nt + 4 * g) = vv;
;             }
;         }
;         __syncthreads();
;         bf16x8 Bv[2];
; #pragma unroll
;         for (int k2 = 0; k2 < 2; ++k2) Bv[k2] = tr2(sVN + (32 * k2 + 8 * g + q4) * 40 + 16 * nt + 4 * p4, sVN + (32 * k2 + 8 * g + 4 + q4) * 40 + 16 * nt + 4 * p4);
;         {
;             f32x4 acc = (f32x4){0.f, 0.f, 0.f, 0.f};
; #pragma unroll
;             for (int ks = 0; ks < 4; ++ks) { const bf16_t* r0 = sQI + (16 * mt + l15) * 136 + 32 * ks + 4 * g; acc = mfma16(Bs[ks], ld4x2(r0, r0 + 16), acc); }
; #pragma unroll
;             for (int k2 = 0; k2 < 2; ++k2) acc = mfma16(Bv[k2], ld8(sAT + (16 * mt + l15) * 72 + 32 * k2 + 8 * g), acc);
;             bf16_t* ob = OG + (size_t)prow(b, dir, 64 * c) * 512 + 128 * h + 32 * cq;
;             u32x2 ov; ov.x = pk2(acc[0], acc[1]); ov.y = pk2(acc[2], acc[3]);
;             *(u32x2*)(ob + sgn * ((16 * mt + l15) * 512) + 16 * nt + 4 * g) = ov;
;         }
; #pragma unroll
;         for (int j = 0; j < 2; ++j) {
;             const int dt = 2 * mt + j;
;             st[j] *= dec;
; #pragma unroll
;             for (int k2 = 0; k2 < 2; ++k2) {
.LBB0_500:
	ds_read_b64_tr_b16 v[226:227], v187 offset:35904
	ds_read_b64_tr_b16 v[224:225], v187 offset:34816
	ds_read_b64_tr_b16 v[228:229], v187 offset:34848
	ds_read_b64_tr_b16 v[232:233], v193 offset:34848
	ds_read_b64_tr_b16 v[230:231], v187 offset:35936
	ds_read_b64_tr_b16 v[234:235], v187 offset:44640
	s_ashr_i32 s43, s42, 31
	s_lshl_b64 s[4:5], s[42:43], 10
	s_nop 2
	v_cvt_pk_bf16_f32 v112, v112, v113
	v_cvt_pk_bf16_f32 v113, v114, v115
	v_lshl_add_u64 v[114:115], v[126:127], 0, s[4:5]
	global_store_dwordx2 v[114:115], v[112:113], off
	ds_read_b64_tr_b16 v[114:115], v187 offset:44608
	ds_read_b64_tr_b16 v[112:113], v193 offset:34816
	v_pk_mul_f32 v[98:99], v[98:99], v[132:133] op_sel_hi:[1,0]
	v_pk_mul_f32 v[96:97], v[96:97], v[132:133] op_sel_hi:[1,0]
	v_pk_mul_f32 v[102:103], v[102:103], v[132:133] op_sel_hi:[1,0]
	v_pk_mul_f32 v[100:101], v[100:101], v[132:133] op_sel_hi:[1,0]
	s_waitcnt lgkmcnt(6)
	v_mfma_f32_16x16x32_bf16 v[96:99], v[224:227], v[108:111], v[96:99]
	s_waitcnt lgkmcnt(0)
	v_mfma_f32_16x16x32_bf16 v[96:99], v[112:115], v[104:107], v[96:99]
	s_mov_b64 s[4:5], 0x6000
	v_lshl_add_u64 v[142:143], v[142:143], 0, s[4:5]
	v_add_u32_e32 v214, 0x6000, v214
	s_mov_b64 s[4:5], 0xc000
	v_mfma_f32_16x16x32_bf16 v[100:103], v[228:231], v[108:111], v[100:103]
	s_add_i32 s21, s21, 12
	s_addk_i32 s22, 0xc0
	s_addk_i32 s24, 0xff40
	v_mfma_f32_16x16x32_bf16 v[100:103], v[232:235], v[104:107], v[100:103]
	v_cvt_pk_bf16_f32 v104, v96, v97
	v_cvt_pk_bf16_f32 v105, v98, v99
	v_lshl_add_u64 v[144:145], v[144:145], 0, s[4:5]
	v_add_u32_e32 v215, 0xc000, v215
	v_lshl_add_u64 v[146:147], v[146:147], 0, s[4:5]
	v_add_u32_e32 v213, 0xc000, v213
	v_lshl_add_u64 v[148:149], v[148:149], 0, s[4:5]
	v_add_u32_e32 v212, 0xc000, v212
	s_nop 2
	v_cvt_pk_bf16_f32 v106, v100, v101
	v_cvt_pk_bf16_f32 v107, v102, v103
	s_cmp_lt_u32 s26, 33
	s_mov_b32 s27, s26
	ds_write_b128 v156, v[104:107]
	s_waitcnt lgkmcnt(0)
	s_cbranch_scc0 .LBB0_640
.LBB0_501:
	s_add_i32 s26, s27, 3
	s_bitcmp1_b32 s26, 0
	s_cselect_b32 s4, 0x10400, 0
	s_add_i32 s28, s57, s4
	v_lshlrev_b32_e32 v198, 1, v118
	v_lshl_add_u32 v190, v120, 1, s28
	v_lshl_add_u32 v192, v122, 1, s28
	v_add3_u32 v194, s28, v119, v116
	v_add3_u32 v191, s28, v161, v198
	s_waitcnt vmcnt(20)
	ds_write_b128 v190, v[0:3]
	s_waitcnt vmcnt(19)
	ds_write_b128 v190, v[4:7] offset:17408
	s_waitcnt vmcnt(18)
	ds_write_b128 v190, v[8:11] offset:34816
	s_waitcnt vmcnt(17)
	ds_write_b128 v192, v[12:15]
	s_waitcnt vmcnt(16)
	ds_write_b128 v192, v[16:19] offset:17408
	s_waitcnt vmcnt(15)
	ds_write_b128 v192, v[24:27] offset:34816
	s_waitcnt vmcnt(14)
	ds_write_b128 v194, v[36:39] offset:52224
	s_and_saveexec_b64 s[40:41], s[0:1]
	ds_write_b128 v191, v[20:23] offset:61440
	s_or_b64 exec, exec, s[40:41]
	s_cmp_gt_u32 s26, 32
	s_waitcnt lgkmcnt(0)
	s_barrier
	ds_read_b128 v[112:115], v117
	ds_read_b128 v[200:203], v117 offset:1024
	ds_read_b128 v[204:207], v117 offset:2048
	ds_read_b128 v[208:211], v117 offset:3072
	v_lshl_add_u32 v134, v121, 1, s28
	v_mov_b32_e32 v104, s21
	ds_read_b32 v132, v104
	v_add_u32_e32 v188, v134, v162
	ds_read2_b64 v[224:227], v188 offset1:4
	ds_read2_b64 v[228:231], v188 offset0:8 offset1:12
	ds_read2_b64 v[232:235], v188 offset0:16 offset1:20
	ds_read2_b64 v[236:239], v188 offset0:24 offset1:28
	v_add_u32_e32 v134, v134, v158
	s_cbranch_scc1 .LBB0_507
	s_add_u32 s100, s98, 0x13f58000
	s_addc_u32 s101, s99, 0
	global_load_dwordx4 v[0:3], v212, s[100:101]
	s_add_u32 s100, s98, 0x15158000
	s_addc_u32 s101, s99, 0
	global_load_dwordx4 v[4:7], v212, s[100:101]
	s_add_u32 s100, s98, 0x16358000
	s_addc_u32 s101, s99, 0
	global_load_dwordx4 v[8:11], v212, s[100:101]
	s_add_u32 s100, s98, 0x13f58000
	s_addc_u32 s101, s99, 0
	global_load_dwordx4 v[12:15], v213, s[100:101]
	s_add_u32 s100, s98, 0x15158000
	s_addc_u32 s101, s99, 0
	global_load_dwordx4 v[16:19], v213, s[100:101]
	s_add_u32 s100, s98, 0x16358000
	s_addc_u32 s101, s99, 0
	global_load_dwordx4 v[24:27], v213, s[100:101]
	s_add_u32 s100, s98, 0x17552000
	s_addc_u32 s101, s99, 0
	global_load_dwordx4 v[36:39], v214, s[100:101]
	s_and_saveexec_b64 s[40:41], s[0:1]
	s_cbranch_execz .LBB0_506
	s_add_u32 s100, s98, 0x12d58000
	s_addc_u32 s101, s99, 0
	global_load_dwordx4 v[20:23], v215, s[100:101] nt

; DI float lo16(unsigned u) { return __uint_as_float(u << 16); }
; DI void gdn_scan_item(const P& p, int item, unsigned char* smem) {
;     ...
;     auto step = [&](GdnRegs& R, int c) {
;         storel(R, c & 1);
;         __syncthreads();
;         loadr(R, c + 3);
;         const bf16_t* sW = (const bf16_t*)(smem + (c & 1) * BUFB); const bf16_t* sQI = sW + 64 * 136; const bf16_t* sKO = sQI + 64 * 136; const bf16_t* sAT = sKO + 64 * 136; const bf16_t* sU = sAT + 64 * 72;
;         const float dec = sdec[c];
;         bf16x8 Bs[4];
; #pragma unroll
;         for (int ks = 0; ks < 4; ++ks) Bs[ks] = __builtin_bit_cast(bf16x8, sBS[(nt * 4 + ks) * 64 + lane]);
;         {
;             f32x4 acc = (f32x4){0.f, 0.f, 0.f, 0.f};
; #pragma unroll
;             for (int ks = 0; ks < 4; ++ks) { const bf16_t* r0 = sW + (16 * mt + l15) * 136 + 32 * ks + 4 * g; acc = mfma16(Bs[ks], ld4x2(r0, r0 + 16), acc); }
;             {
;                 const u32x2 uu = *(const u32x2*)(sU + (16 * mt + l15) * 40 + 16 * nt + 4 * g);
;                 u32x2 vv; vv.x = pk2(lo16(uu.x) - acc[0], hi16(uu.x) - acc[1]); vv.y = pk2(lo16(uu.y) - acc[2], hi16(uu.y) - acc[3]);
;                 *(u32x2*)(sVN + (16 * mt + l15) * 40 + 16 * nt + 4 * g) = vv;
;             }
;         }
;         __syncthreads();
;         bf16x8 Bv[2];
; #pragma unroll
;         for (int k2 = 0; k2 < 2; ++k2) Bv[k2] = tr2(sVN + (32 * k2 + 8 * g + q4) * 40 + 16 * nt + 4 * p4, sVN + (32 * k2 + 8 * g + 4 + q4) * 40 + 16 * nt + 4 * p4);
;         {
;             f32x4 acc = (f32x4){0.f, 0.f, 0.f, 0.f};
; #pragma unroll
;             for (int ks = 0; ks < 4; ++ks) { const bf16_t* r0 = sQI + (16 * mt + l15) * 136 + 32 * ks + 4 * g; acc = mfma16(Bs[ks], ld4x2(r0, r0 + 16), acc); }
; #pragma unroll
;             for (int k2 = 0; k2 < 2; ++k2) acc = mfma16(Bv[k2], ld8(sAT + (16 * mt + l15) * 72 + 32 * k2 + 8 * g), acc);
;             bf16_t* ob = OG + (size_t)prow(b, dir, 64 * c) * 512 + 128 * h + 32 * cq;
;             u32x2 ov; ov.x = pk2(acc[0], acc[1]); ov.y = pk2(acc[2], acc[3]);
;             *(u32x2*)(ob + sgn * ((16 * mt + l15) * 512) + 16 * nt + 4 * g) = ov;
;         }
; #pragma unroll
;         for (int j = 0; j < 2; ++j) {
;             const int dt = 2 * mt + j;
;             st[j] *= dec;
; #pragma unroll
;             for (int k2 = 0; k2 < 2; ++k2) {
.LBB0_511:
	v_lshl_add_u32 v134, v125, 1, s28
	v_lshlrev_b32_e32 v197, 1, v157
	v_add3_u32 v187, v134, v185, v197
	ds_read_b64_tr_b16 v[226:227], v187 offset:35904
	ds_read_b64_tr_b16 v[224:225], v187 offset:34816
	ds_read_b64_tr_b16 v[230:231], v187 offset:44608
	ds_read_b64_tr_b16 v[234:235], v187 offset:35936
	ds_read_b64_tr_b16 v[232:233], v187 offset:34848
	ds_read_b64_tr_b16 v[238:239], v187 offset:44640
	v_add3_u32 v193, v134, v186, v197
	ds_read_b64_tr_b16 v[228:229], v193 offset:34816
	ds_read_b64_tr_b16 v[236:237], v193 offset:34848
	v_pk_mul_f32 v[98:99], v[98:99], v[132:133] op_sel_hi:[1,0]
	v_pk_mul_f32 v[96:97], v[96:97], v[132:133] op_sel_hi:[1,0]
	v_pk_mul_f32 v[102:103], v[102:103], v[132:133] op_sel_hi:[1,0]
	v_pk_mul_f32 v[100:101], v[100:101], v[132:133] op_sel_hi:[1,0]
	s_waitcnt lgkmcnt(6)
	v_mfma_f32_16x16x32_bf16 v[96:99], v[224:227], v[108:111], v[96:99]
	s_ashr_i32 s41, s40, 31
	s_lshl_b64 s[4:5], s[40:41], 10
	s_waitcnt lgkmcnt(3)
	v_mfma_f32_16x16x32_bf16 v[100:103], v[232:235], v[108:111], v[100:103]
	s_bitcmp1_b32 s27, 0
	v_lshl_add_u64 v[108:109], v[126:127], 0, s[4:5]
	s_cselect_b32 s4, 0x10400, 0
	s_waitcnt lgkmcnt(1)
	v_mfma_f32_16x16x32_bf16 v[96:99], v[228:231], v[104:107], v[96:99]
	s_add_i32 s27, s57, s4
	v_cvt_pk_bf16_f32 v112, v112, v113
	v_cvt_pk_bf16_f32 v113, v114, v115
	s_waitcnt lgkmcnt(0)
	v_mfma_f32_16x16x32_bf16 v[100:103], v[236:239], v[104:107], v[100:103]
	global_store_dwordx2 v[108:109], v[112:113], off
	s_nop 1
	v_cvt_pk_bf16_f32 v104, v96, v97
	v_cvt_pk_bf16_f32 v105, v98, v99
	s_nop 2
	v_cvt_pk_bf16_f32 v106, v100, v101
	v_cvt_pk_bf16_f32 v107, v102, v103
	ds_write_b128 v156, v[104:107]
	v_lshl_add_u32 v104, v120, 1, s27
	s_waitcnt vmcnt(14)
	ds_write_b128 v104, v[28:31]
	s_waitcnt vmcnt(13)
	ds_write_b128 v104, v[32:35] offset:17408
	s_waitcnt vmcnt(12)
	ds_write_b128 v104, v[40:43] offset:34816
	v_lshl_add_u32 v104, v122, 1, s27
	s_waitcnt vmcnt(11)
	ds_write_b128 v104, v[48:51]
	s_waitcnt vmcnt(10)
	ds_write_b128 v104, v[52:55] offset:17408
	s_waitcnt vmcnt(9)
	ds_write_b128 v104, v[64:67] offset:34816
	v_add3_u32 v104, s27, v119, v116
	s_waitcnt vmcnt(3)
	ds_write_b128 v104, v[72:75] offset:52224
	s_waitcnt lgkmcnt(0)
	s_and_saveexec_b64 s[40:41], s[0:1]
	v_add3_u32 v104, s27, v161, v198
	ds_write_b128 v104, v[44:47] offset:61440
	s_or_b64 exec, exec, s[40:41]
	s_cmp_gt_u32 s26, 31
	v_readlane_b32 s12, v254, 56
	s_waitcnt lgkmcnt(0)
	s_barrier
	ds_read_b128 v[110:113], v117
	ds_read_b128 v[200:203], v117 offset:1024
	ds_read_b128 v[204:207], v117 offset:2048
	ds_read_b128 v[208:211], v117 offset:3072
	v_lshl_add_u32 v109, v121, 1, s27
	v_mov_b32_e32 v104, s21
	ds_read_b32 v108, v104 offset:4
	v_add_u32_e32 v132, v109, v162
	ds_read2_b64 v[224:227], v132 offset1:4
	ds_read2_b64 v[228:231], v132 offset0:8 offset1:12
	ds_read2_b64 v[236:239], v132 offset0:16 offset1:20
	ds_read2_b64 v[240:243], v132 offset0:24 offset1:28
	v_add_u32_e32 v109, v109, v158
	v_readlane_b32 s13, v254, 57
	s_cbranch_scc1 .LBB0_517
	s_add_u32 s100, s98, 0x13f5c000
	s_addc_u32 s101, s99, 0
	global_load_dwordx4 v[28:31], v212, s[100:101]
	s_add_u32 s100, s98, 0x1515c000
	s_addc_u32 s101, s99, 0
	global_load_dwordx4 v[32:35], v212, s[100:101]
	s_add_u32 s100, s98, 0x1635c000
	s_addc_u32 s101, s99, 0
	global_load_dwordx4 v[40:43], v212, s[100:101]
	s_add_u32 s100, s98, 0x13f5c000
	s_addc_u32 s101, s99, 0
	global_load_dwordx4 v[48:51], v213, s[100:101]
	s_add_u32 s100, s98, 0x1515c000
	s_addc_u32 s101, s99, 0
	global_load_dwordx4 v[52:55], v213, s[100:101]
	s_add_u32 s100, s98, 0x1635c000
	s_addc_u32 s101, s99, 0
	global_load_dwordx4 v[64:67], v213, s[100:101]
	s_add_u32 s100, s98, 0x17554000
	s_addc_u32 s101, s99, 0
	global_load_dwordx4 v[72:75], v214, s[100:101]
	s_and_saveexec_b64 s[40:41], s[0:1]
	s_cbranch_execz .LBB0_516
	s_add_u32 s100, s98, 0x12d5c000
	s_addc_u32 s101, s99, 0
	global_load_dwordx4 v[44:47], v215, s[100:101] nt

; DI float lo16(unsigned u) { return __uint_as_float(u << 16); }
; DI void gdn_scan_item(const P& p, int item, unsigned char* smem) {
;     ...
;     auto step = [&](GdnRegs& R, int c) {
;         storel(R, c & 1);
;         __syncthreads();
;         loadr(R, c + 3);
;         const bf16_t* sW = (const bf16_t*)(smem + (c & 1) * BUFB); const bf16_t* sQI = sW + 64 * 136; const bf16_t* sKO = sQI + 64 * 136; const bf16_t* sAT = sKO + 64 * 136; const bf16_t* sU = sAT + 64 * 72;
;         const float dec = sdec[c];
;         bf16x8 Bs[4];
; #pragma unroll
;         for (int ks = 0; ks < 4; ++ks) Bs[ks] = __builtin_bit_cast(bf16x8, sBS[(nt * 4 + ks) * 64 + lane]);
;         {
;             f32x4 acc = (f32x4){0.f, 0.f, 0.f, 0.f};
; #pragma unroll
;             for (int ks = 0; ks < 4; ++ks) { const bf16_t* r0 = sW + (16 * mt + l15) * 136 + 32 * ks + 4 * g; acc = mfma16(Bs[ks], ld4x2(r0, r0 + 16), acc); }
;             {
;                 const u32x2 uu = *(const u32x2*)(sU + (16 * mt + l15) * 40 + 16 * nt + 4 * g);
;                 u32x2 vv; vv.x = pk2(lo16(uu.x) - acc[0], hi16(uu.x) - acc[1]); vv.y = pk2(lo16(uu.y) - acc[2], hi16(uu.y) - acc[3]);
;                 *(u32x2*)(sVN + (16 * mt + l15) * 40 + 16 * nt + 4 * g) = vv;
;             }
;         }
;         __syncthreads();
;         bf16x8 Bv[2];
; #pragma unroll
;         for (int k2 = 0; k2 < 2; ++k2) Bv[k2] = tr2(sVN + (32 * k2 + 8 * g + q4) * 40 + 16 * nt + 4 * p4, sVN + (32 * k2 + 8 * g + 4 + q4) * 40 + 16 * nt + 4 * p4);
;         {
;             f32x4 acc = (f32x4){0.f, 0.f, 0.f, 0.f};
; #pragma unroll
;             for (int ks = 0; ks < 4; ++ks) { const bf16_t* r0 = sQI + (16 * mt + l15) * 136 + 32 * ks + 4 * g; acc = mfma16(Bs[ks], ld4x2(r0, r0 + 16), acc); }
; #pragma unroll
;             for (int k2 = 0; k2 < 2; ++k2) acc = mfma16(Bv[k2], ld8(sAT + (16 * mt + l15) * 72 + 32 * k2 + 8 * g), acc);
;             bf16_t* ob = OG + (size_t)prow(b, dir, 64 * c) * 512 + 128 * h + 32 * cq;
;             u32x2 ov; ov.x = pk2(acc[0], acc[1]); ov.y = pk2(acc[2], acc[3]);
;             *(u32x2*)(ob + sgn * ((16 * mt + l15) * 512) + 16 * nt + 4 * g) = ov;
;         }
; #pragma unroll
;         for (int j = 0; j < 2; ++j) {
;             const int dt = 2 * mt + j;
;             st[j] *= dec;
; #pragma unroll
;             for (int k2 = 0; k2 < 2; ++k2) {
.LBB0_517:
	s_waitcnt lgkmcnt(3)
	v_mfma_f32_16x16x32_bf16 v[104:107], v[110:113], v[224:227], 0
	v_add3_u32 v114, v109, v163, v162
	ds_read_b64 v[232:233], v114 offset:61440
	v_add_u32_e32 v109, v109, v159
	s_waitcnt lgkmcnt(3)
	v_mfma_f32_16x16x32_bf16 v[104:107], v[200:203], v[228:231], v[104:107]
	v_add3_u32 v109, v109, v160, v199
	s_waitcnt lgkmcnt(0)
	v_lshlrev_b32_e32 v134, 16, v232
	v_mfma_f32_16x16x32_bf16 v[104:107], v[204:207], v[236:239], v[104:107]
	v_and_b32_e32 v114, 0xffff0000, v232
	s_sub_i32 s4, s22, 64
	v_mfma_f32_16x16x32_bf16 v[104:107], v[208:211], v[240:243], v[104:107]
	s_add_i32 s5, s22, 0xfffffec0
	s_cmp_lt_u32 s26, 3
	s_movk_i32 s6, 0x8ff
	s_nop 4
	v_sub_f32_e32 v104, v134, v104
	v_sub_f32_e32 v105, v114, v105
	v_cvt_pk_bf16_f32 v104, v104, v105
	v_lshlrev_b32_e32 v105, 16, v233
	v_sub_f32_e32 v105, v105, v106
	v_and_b32_e32 v106, 0xffff0000, v233
	v_sub_f32_e32 v106, v106, v107
	v_cvt_pk_bf16_f32 v105, v105, v106
	v_add_u32_e32 v114, 0x4000, v132
	ds_write_b64 v123, v[104:105]
	s_waitcnt lgkmcnt(0)
	s_barrier
	ds_read_b64_tr_b16 v[224:225], v164
	ds_read_b64_tr_b16 v[226:227], v165
	ds_read_b64_tr_b16 v[228:229], v183
	ds_read_b64_tr_b16 v[230:231], v184
	ds_read2_b64 v[232:235], v114 offset0:128 offset1:132
	ds_read2_b64 v[236:239], v114 offset0:136 offset1:140
	ds_read2_b64 v[240:243], v114 offset0:144 offset1:148
	ds_read2_b64 v[244:247], v114 offset0:152 offset1:156
	ds_read_b128 v[248:251], v109 offset:52224
	s_waitcnt lgkmcnt(4)
	v_mfma_f32_16x16x32_bf16 v[110:113], v[110:113], v[232:235], 0
	ds_read_b128 v[232:235], v109 offset:52288
	s_cselect_b32 s6, 0xff, s6
	s_cselect_b32 s7, s4, s5
	s_waitcnt lgkmcnt(4)
	v_mfma_f32_16x16x32_bf16 v[110:113], v[200:203], v[236:239], v[110:113]
	s_cselect_b32 s8, s3, s2
	s_add_i32 s4, s6, s24
	s_waitcnt lgkmcnt(3)
	v_mfma_f32_16x16x32_bf16 v[110:113], v[204:207], v[240:243], v[110:113]
	s_add_i32 s6, s4, 0xfffff741
	s_and_b64 s[4:5], s[38:39], exec
	s_waitcnt lgkmcnt(2)
	v_mfma_f32_16x16x32_bf16 v[110:113], v[208:211], v[244:247], v[110:113]
	s_cselect_b32 s4, s7, s6
	s_add_i32 s4, s4, s8
	s_waitcnt lgkmcnt(1)
	v_mfma_f32_16x16x32_bf16 v[110:113], v[224:227], v[248:251], v[110:113]
	s_ashr_i32 s5, s4, 31
	s_lshl_b64 s[4:5], s[4:5], 10
	s_waitcnt lgkmcnt(0)
	v_mfma_f32_16x16x32_bf16 v[110:113], v[228:231], v[232:235], v[110:113]
	v_mul_f32_e64 v98, v98, v108
	v_mul_f32_e64 v99, v99, v108
	v_pk_mul_f32 v[96:97], v[96:97], v[108:109] op_sel_hi:[1,0]
	v_lshl_add_u32 v109, v125, 1, s27
	s_nop 3
	v_cvt_pk_bf16_f32 v110, v110, v111
	v_cvt_pk_bf16_f32 v111, v112, v113
	v_lshl_add_u64 v[112:113], v[126:127], 0, s[4:5]
	global_store_dwordx2 v[112:113], v[110:111], off
	v_add3_u32 v114, v109, v185, v197
	ds_read_b64_tr_b16 v[238:239], v114 offset:35904
	ds_read_b64_tr_b16 v[236:237], v114 offset:34816
	ds_read_b64_tr_b16 v[240:241], v114 offset:34848
	ds_read_b64_tr_b16 v[246:247], v114 offset:44608
	ds_read_b64_tr_b16 v[242:243], v114 offset:35936
	ds_read_b64_tr_b16 v[250:251], v114 offset:44640
	s_waitcnt lgkmcnt(4)
	v_mfma_f32_16x16x32_bf16 v[96:99], v[236:239], v[224:227], v[96:99]
	v_add3_u32 v109, v109, v186, v197
	ds_read_b64_tr_b16 v[244:245], v109 offset:34816
	ds_read_b64_tr_b16 v[248:249], v109 offset:34848
	v_pk_mul_f32 v[102:103], v[102:103], v[108:109] op_sel_hi:[1,0]
	v_pk_mul_f32 v[100:101], v[100:101], v[108:109] op_sel_hi:[1,0]
	s_waitcnt lgkmcnt(1)
	v_mfma_f32_16x16x32_bf16 v[96:99], v[244:247], v[228:231], v[96:99]
	v_mfma_f32_16x16x32_bf16 v[100:103], v[240:243], v[224:227], v[100:103]
	s_waitcnt lgkmcnt(0)
	v_mfma_f32_16x16x32_bf16 v[100:103], v[248:251], v[228:231], v[100:103]
	s_nop 3
	s_nop 0
	v_cvt_pk_bf16_f32 v104, v96, v97
	v_cvt_pk_bf16_f32 v105, v98, v99
	s_nop 1
	v_cvt_pk_bf16_f32 v106, v100, v101
	v_cvt_pk_bf16_f32 v107, v102, v103
	ds_write_b128 v156, v[104:107]
	s_waitcnt vmcnt(8)
	ds_write_b128 v190, v[56:59]
	s_waitcnt vmcnt(7)
	ds_write_b128 v190, v[60:63] offset:17408
	s_waitcnt vmcnt(6)
	ds_write_b128 v190, v[68:71] offset:34816
	s_waitcnt vmcnt(5)
	ds_write_b128 v192, v[76:79]
	s_waitcnt vmcnt(4)
	ds_write_b128 v192, v[80:83] offset:17408
	s_waitcnt vmcnt(3)
	ds_write_b128 v192, v[84:87] offset:34816
	s_waitcnt vmcnt(2)
	ds_write_b128 v194, v[92:95] offset:52224
	s_waitcnt lgkmcnt(0)
	s_and_saveexec_b64 s[40:41], s[0:1]
	ds_write_b128 v191, v[88:91] offset:61440
	s_or_b64 exec, exec, s[40:41]
	s_cmp_gt_u32 s26, 30
	s_waitcnt lgkmcnt(0)
	s_barrier
	ds_read_b128 v[112:115], v117
	ds_read_b128 v[248:251], v117 offset:1024
	ds_read_b128 v[198:201], v117 offset:2048
	ds_read_b128 v[202:205], v117 offset:3072
	ds_read2_b64 v[224:227], v188 offset1:4
	ds_read2_b64 v[228:231], v188 offset0:8 offset1:12
	ds_read2_b64 v[232:235], v188 offset0:16 offset1:20
	ds_read2_b64 v[236:239], v188 offset0:24 offset1:28
	ds_read_b64 v[240:241], v195 offset:61440
	v_mov_b32_e32 v104, s21
	ds_read_b32 v132, v104 offset:8
	s_cbranch_scc1 .LBB0_523
	s_add_u32 s100, s98, 0x13f60000
	s_addc_u32 s101, s99, 0
	global_load_dwordx4 v[56:59], v212, s[100:101]
	s_add_u32 s100, s98, 0x15160000
	s_addc_u32 s101, s99, 0
	global_load_dwordx4 v[60:63], v212, s[100:101]
	s_add_u32 s100, s98, 0x16360000
	s_addc_u32 s101, s99, 0
	global_load_dwordx4 v[68:71], v212, s[100:101]
	s_add_u32 s100, s98, 0x13f60000
	s_addc_u32 s101, s99, 0
	global_load_dwordx4 v[76:79], v213, s[100:101]
	s_add_u32 s100, s98, 0x15160000
	s_addc_u32 s101, s99, 0
	global_load_dwordx4 v[80:83], v213, s[100:101]
	s_add_u32 s100, s98, 0x16360000
	s_addc_u32 s101, s99, 0
	global_load_dwordx4 v[84:87], v213, s[100:101]
	s_add_u32 s100, s98, 0x17556000
	s_addc_u32 s101, s99, 0
	global_load_dwordx4 v[92:95], v214, s[100:101]
	s_and_saveexec_b64 s[40:41], s[0:1]
	s_cbranch_execz .LBB0_522
	s_add_u32 s100, s98, 0x12d60000
	s_addc_u32 s101, s99, 0
	global_load_dwordx4 v[88:91], v215, s[100:101] nt
